# trim33 + attention row-sum split into two independent f32 accumulators (same add count, dependency distance 2)
# speedup vs baseline: 1.0025x; 1.0011x over previous
.Latt_head:
	s_lshl_b32 s14, s14, 1
	v_add_u32_e32 v217, s14, v244
	ds_read_b64_tr_b16 v[208:209], v217 offset:24576
	ds_read_b64_tr_b16 v[210:211], v217 offset:25088
	v_add_f32_e32 v224, v96, v97
	v_add_f32_e32 v225, v98, v99
	v_add_f32_e32 v224, v100, v224
	v_add_f32_e32 v225, v101, v225
	v_cvt_pk_bf16_f32 v164, v96, v97
	v_cvt_pk_bf16_f32 v165, v98, v99
	ds_read_b64_tr_b16 v[96:97], v217 offset:28672
	ds_read_b64_tr_b16 v[98:99], v217 offset:29184
	v_add_f32_e32 v224, v102, v224
	v_add_f32_e32 v225, v103, v225
	v_add_f32_e32 v224, v104, v224
	v_add_f32_e32 v225, v105, v225
	v_mfma_f32_32x32x16_bf16 v[112:127], v[200:203], v[172:175], v[64:79]
	v_cvt_pk_bf16_f32 v166, v100, v101
	v_cvt_pk_bf16_f32 v167, v102, v103
	ds_read_b64_tr_b16 v[100:101], v217 offset:25600
	ds_read_b64_tr_b16 v[102:103], v217 offset:26112
	v_mfma_f32_32x32x16_bf16 v[128:143], v[196:199], v[168:171], v[128:143]
	v_add_f32_e32 v224, v106, v224
	v_add_f32_e32 v225, v107, v225
	v_add_f32_e32 v224, v108, v224
	v_add_f32_e32 v225, v109, v225
	v_cvt_pk_bf16_f32 v156, v104, v105
	v_cvt_pk_bf16_f32 v157, v106, v107
	ds_read_b64_tr_b16 v[104:105], v217 offset:29696
	ds_read_b64_tr_b16 v[106:107], v217 offset:30208
	v_mfma_f32_32x32x16_bf16 v[112:127], v[192:195], v[168:171], v[112:127]
	v_add_f32_e32 v224, v110, v224
	v_add_f32_e32 v225, v111, v225
	v_add_f32_e32 v224, v80, v224
	v_add_f32_e32 v225, v81, v225
	v_cvt_pk_bf16_f32 v158, v108, v109
	v_cvt_pk_bf16_f32 v159, v110, v111
	ds_read_b64_tr_b16 v[108:109], v217 offset:26624
	ds_read_b64_tr_b16 v[110:111], v217 offset:27136
	v_mfma_f32_32x32x16_bf16 v[128:143], v[188:191], v[160:163], v[128:143]
	v_add_f32_e32 v224, v82, v224
	v_add_f32_e32 v225, v83, v225
	v_add_f32_e32 v224, v84, v224
	v_add_f32_e32 v225, v85, v225
	v_cvt_pk_bf16_f32 v148, v80, v81
	v_cvt_pk_bf16_f32 v149, v82, v83
	ds_read_b64_tr_b16 v[80:81], v217 offset:30720
	ds_read_b64_tr_b16 v[82:83], v217 offset:31232
	v_mfma_f32_32x32x16_bf16 v[112:127], v[184:187], v[160:163], v[112:127]
	v_add_f32_e32 v224, v86, v224
	v_add_f32_e32 v225, v87, v225
	v_add_f32_e32 v224, v88, v224
	v_add_f32_e32 v225, v89, v225
	v_cvt_pk_bf16_f32 v150, v84, v85
	v_cvt_pk_bf16_f32 v151, v86, v87
	ds_read_b64_tr_b16 v[84:85], v217 offset:27648
	ds_read_b64_tr_b16 v[86:87], v217 offset:28160
	v_mfma_f32_32x32x16_bf16 v[128:143], v[180:183], v[152:155], v[128:143]
	v_add_f32_e32 v224, v90, v224
	v_add_f32_e32 v225, v91, v225
	v_add_f32_e32 v224, v92, v224
	v_add_f32_e32 v225, v93, v225
	v_cvt_pk_bf16_f32 v144, v88, v89
	v_cvt_pk_bf16_f32 v145, v90, v91
	ds_read_b64_tr_b16 v[88:89], v217 offset:31744
	ds_read_b64_tr_b16 v[90:91], v217 offset:32256
	v_mfma_f32_32x32x16_bf16 v[112:127], v[176:179], v[152:155], v[112:127]
	v_add_f32_e32 v224, v94, v224
	v_add_f32_e32 v225, v95, v225
	v_add_f32_e32 v176, v224, v225
	v_cvt_pk_bf16_f32 v146, v92, v93
	v_cvt_pk_bf16_f32 v147, v94, v95
	s_add_i32 m0, s24, s63
	s_mov_b32 s14, s32
	s_mov_b32 s15, s70
	global_load_lds_dwordx4 v212, s[14:15]
	s_lshl_b32 s14, s22, 1
	s_add_i32 s14, s14, s64
	s_mov_b32 m0, s14
	s_add_i32 s14, s14, 0x1f80
	global_load_lds_dwordx4 v226, s[98:99]
	s_mov_b32 m0, s14
	s_nop 0
	global_load_lds_dwordx4 v226, s[98:99] offset:128
	s_waitcnt lgkmcnt(12)
	v_mfma_f32_32x32x16_bf16 v[32:47], v[164:167], v[208:211], v[32:47]
	v_max_f32_e32 v222, v128, v129
	v_max3_f32 v223, v130, v131, v113
	v_max3_f32 v222, v222, v112, v114
	v_max3_f32 v222, v222, v115, v132
	ds_read_b64_tr_b16 v[92:93], v217 offset:32768
	ds_read_b64_tr_b16 v[94:95], v217 offset:33280
	v_mfma_f32_32x32x16_bf16 v[48:63], v[164:167], v[96:99], v[48:63]
	v_max3_f32 v223, v223, v134, v135
	v_max3_f32 v222, v222, v133, v116
	v_max3_f32 v223, v223, v118, v119
	v_max3_f32 v222, v222, v117, v136
	ds_read_b64_tr_b16 v[96:97], v217 offset:36864
	ds_read_b64_tr_b16 v[98:99], v217 offset:37376
	s_waitcnt lgkmcnt(12)
	v_mfma_f32_32x32x16_bf16 v[32:47], v[156:159], v[100:103], v[32:47]
	v_max3_f32 v223, v223, v138, v139
	v_max3_f32 v222, v222, v137, v120
	v_max3_f32 v223, v223, v122, v123
	v_max3_f32 v222, v222, v121, v140
	ds_read_b64_tr_b16 v[100:101], v217 offset:33792
	ds_read_b64_tr_b16 v[102:103], v217 offset:34304
	v_mfma_f32_32x32x16_bf16 v[48:63], v[156:159], v[104:107], v[48:63]
	v_max3_f32 v223, v223, v142, v143
	v_max3_f32 v222, v222, v141, v124
	v_max3_f32 v223, v223, v126, v127
	v_max3_f32 v222, v222, v125, v223
	ds_read_b64_tr_b16 v[104:105], v217 offset:37888
	ds_read_b64_tr_b16 v[106:107], v217 offset:38400
	s_waitcnt lgkmcnt(12)
	v_mfma_f32_32x32x16_bf16 v[32:47], v[148:151], v[108:111], v[32:47]
	v_mov_b32_e32 v223, v222
	v_add_f32_e32 v215, v249, v176
	s_nop 0
	v_permlane32_swap_b32_e32 v222, v223
	v_max_f32_e32 v222, v222, v223
	v_cmp_lt_f32_e32 vcc, s33, v222
	s_nop 0
	s_mov_b64 s[20:21], vcc
	s_cbranch_vccnz .LBB0_318

.LBB0_313:
	v_mfma_f32_32x32x16_bf16 v[96:111], v[80:83], v[172:175], v[64:79]
	s_add_i32 s14, s22, 0x2000
	s_cmpk_lg_i32 s22, 0x4000
	s_cselect_b32 s66, s14, 0
	s_lshl_b32 s14, s24, 1
	v_add_u32_e32 v209, s14, v244
	ds_read_b64_tr_b16 v[188:189], v209 offset:24576
	ds_read_b64_tr_b16 v[190:191], v209 offset:25088
	v_add_f32_e32 v222, v128, v129
	v_add_f32_e32 v223, v130, v131
	v_add_f32_e32 v222, v132, v222
	v_add_f32_e32 v223, v133, v223
	v_cvt_pk_bf16_f32 v164, v128, v129
	v_cvt_pk_bf16_f32 v165, v130, v131
	ds_read_b64_tr_b16 v[128:129], v209 offset:28672
	ds_read_b64_tr_b16 v[130:131], v209 offset:29184
	v_add_f32_e32 v222, v134, v222
	v_add_f32_e32 v223, v135, v223
	v_add_f32_e32 v222, v136, v222
	v_add_f32_e32 v223, v137, v223
	v_mfma_f32_32x32x16_bf16 v[80:95], v[200:203], v[172:175], v[64:79]
	v_cvt_pk_bf16_f32 v166, v132, v133
	v_cvt_pk_bf16_f32 v167, v134, v135
	ds_read_b64_tr_b16 v[132:133], v209 offset:25600
	ds_read_b64_tr_b16 v[134:135], v209 offset:26112
	v_mfma_f32_32x32x16_bf16 v[96:111], v[204:207], v[168:171], v[96:111]
	v_add_f32_e32 v222, v138, v222
	v_add_f32_e32 v223, v139, v223
	v_add_f32_e32 v222, v140, v222
	v_add_f32_e32 v223, v141, v223
	v_cvt_pk_bf16_f32 v156, v136, v137
	v_cvt_pk_bf16_f32 v157, v138, v139
	ds_read_b64_tr_b16 v[136:137], v209 offset:29696
	ds_read_b64_tr_b16 v[138:139], v209 offset:30208
	v_mfma_f32_32x32x16_bf16 v[80:95], v[196:199], v[168:171], v[80:95]
	v_add_f32_e32 v222, v142, v222
	v_add_f32_e32 v223, v143, v223
	v_add_f32_e32 v222, v112, v222
	v_add_f32_e32 v223, v113, v223
	v_cvt_pk_bf16_f32 v158, v140, v141
	v_cvt_pk_bf16_f32 v159, v142, v143
	ds_read_b64_tr_b16 v[140:141], v209 offset:26624
	ds_read_b64_tr_b16 v[142:143], v209 offset:27136
	v_mfma_f32_32x32x16_bf16 v[96:111], v[192:195], v[160:163], v[96:111]
	v_add_f32_e32 v222, v114, v222
	v_add_f32_e32 v223, v115, v223
	v_add_f32_e32 v222, v116, v222
	v_add_f32_e32 v223, v117, v223
	v_cvt_pk_bf16_f32 v148, v112, v113
	v_cvt_pk_bf16_f32 v149, v114, v115
	ds_read_b64_tr_b16 v[112:113], v209 offset:30720
	ds_read_b64_tr_b16 v[114:115], v209 offset:31232
	v_mfma_f32_32x32x16_bf16 v[80:95], v[184:187], v[160:163], v[80:95]
	v_add_f32_e32 v222, v118, v222
	v_add_f32_e32 v223, v119, v223
	v_add_f32_e32 v222, v120, v222
	v_add_f32_e32 v223, v121, v223
	v_cvt_pk_bf16_f32 v150, v116, v117
	v_cvt_pk_bf16_f32 v151, v118, v119
	ds_read_b64_tr_b16 v[116:117], v209 offset:27648
	ds_read_b64_tr_b16 v[118:119], v209 offset:28160
	v_mfma_f32_32x32x16_bf16 v[96:111], v[180:183], v[152:155], v[96:111]
	v_add_f32_e32 v222, v122, v222
	v_add_f32_e32 v223, v123, v223
	v_add_f32_e32 v222, v124, v222
	v_add_f32_e32 v223, v125, v223
	v_cvt_pk_bf16_f32 v144, v120, v121
	v_cvt_pk_bf16_f32 v145, v122, v123
	ds_read_b64_tr_b16 v[120:121], v209 offset:31744
	ds_read_b64_tr_b16 v[122:123], v209 offset:32256
	v_mfma_f32_32x32x16_bf16 v[80:95], v[176:179], v[152:155], v[80:95]
	v_add_f32_e32 v222, v126, v222
	v_add_f32_e32 v223, v127, v223
	v_add_f32_e32 v176, v222, v223
	v_cvt_pk_bf16_f32 v146, v124, v125
	v_cvt_pk_bf16_f32 v147, v126, v127
	s_add_i32 m0, s22, s63
	s_add_u32 s14, s32, 0x20000
	s_addc_u32 s15, s70, 0
	global_load_lds_dwordx4 v212, s[14:15]
	s_lshl_b32 s20, s66, 1
	s_add_i32 s20, s20, s64
	s_add_u32 s14, s98, 0x20000
	s_addc_u32 s15, s99, 0
	s_mov_b32 m0, s20
	s_add_i32 s20, s20, 0x1f80
	global_load_lds_dwordx4 v226, s[14:15]
	s_mov_b32 m0, s20
	s_nop 0
	global_load_lds_dwordx4 v226, s[14:15] offset:128
	s_waitcnt lgkmcnt(12)
	v_mfma_f32_32x32x16_bf16 v[32:47], v[164:167], v[188:191], v[32:47]
	v_max_f32_e32 v224, v96, v97
	v_max3_f32 v225, v98, v99, v81
	v_max3_f32 v224, v224, v80, v82
	v_max3_f32 v224, v224, v83, v100
	ds_read_b64_tr_b16 v[124:125], v209 offset:32768
	ds_read_b64_tr_b16 v[126:127], v209 offset:33280
	v_mfma_f32_32x32x16_bf16 v[48:63], v[164:167], v[128:131], v[48:63]
	v_max3_f32 v225, v225, v102, v103
	v_max3_f32 v224, v224, v101, v84
	v_max3_f32 v225, v225, v86, v87
	v_max3_f32 v224, v224, v85, v104
	ds_read_b64_tr_b16 v[128:129], v209 offset:36864
	ds_read_b64_tr_b16 v[130:131], v209 offset:37376
	s_waitcnt lgkmcnt(12)
	v_mfma_f32_32x32x16_bf16 v[32:47], v[156:159], v[132:135], v[32:47]
	v_max3_f32 v225, v225, v106, v107
	v_max3_f32 v224, v224, v105, v88
	v_max3_f32 v225, v225, v90, v91
	v_max3_f32 v224, v224, v89, v108
	ds_read_b64_tr_b16 v[132:133], v209 offset:33792
	ds_read_b64_tr_b16 v[134:135], v209 offset:34304
	v_mfma_f32_32x32x16_bf16 v[48:63], v[156:159], v[136:139], v[48:63]
	v_max3_f32 v225, v225, v110, v111
	v_max3_f32 v224, v224, v109, v92
	v_max3_f32 v225, v225, v94, v95
	v_max3_f32 v224, v224, v93, v225
	ds_read_b64_tr_b16 v[136:137], v209 offset:37888
	ds_read_b64_tr_b16 v[138:139], v209 offset:38400
	s_waitcnt lgkmcnt(12)
	v_mfma_f32_32x32x16_bf16 v[32:47], v[148:151], v[140:143], v[32:47]
	v_mov_b32_e32 v225, v224
	v_add_f32_e32 v249, v215, v176
	s_nop 0
	v_permlane32_swap_b32_e32 v224, v225
	v_max_f32_e32 v224, v224, v225
	v_cmp_lt_f32_e32 vcc, s33, v224
	s_nop 0
	s_mov_b64 s[20:21], vcc
	s_cbranch_vccnz .LBB0_321
